# P2c combine phase: all loads of a row issued at the top of the iteration instead of 3-4 dependent load stages
# speedup vs baseline: 1.0425x; 1.0029x over previous
.LBB0_528:
	s_bitcmp0_b32 s4, 10
	s_cbranch_scc1 .Lp2c_nosplit
	v_lshl_add_u64 v[148:149], s[0:1], 0, v[10:11]
	v_add_co_u32_e32 v150, vcc, 0x3a00000, v148
	s_nop 1
	v_addc_co_u32_e32 v151, vcc, 0, v149, vcc
	global_load_dwordx2 v[130:131], v[150:151], off
	v_add_co_u32_e32 v150, vcc, 0x3e00000, v148
	s_nop 1
	v_addc_co_u32_e32 v151, vcc, 0, v149, vcc
	global_load_dwordx2 v[134:135], v[150:151], off
	v_add_co_u32_e32 v150, vcc, 0x4600000, v148
	s_nop 1
	v_addc_co_u32_e32 v151, vcc, 0, v149, vcc
	global_load_dwordx2 v[136:137], v[150:151], off
	v_lshl_add_u64 v[150:151], s[0:1], 0, v[14:15]
	v_add_co_u32_e32 v150, vcc, 0x5a00000, v150
	s_nop 1
	v_addc_co_u32_e32 v151, vcc, 0, v151, vcc
	global_load_dwordx2 v[132:133], v[150:151], off offset:1024
	v_lshl_add_u64 v[150:151], s[0:1], 0, v[12:13]
	v_add_co_u32_e32 v150, vcc, 0x7680000, v150
	s_nop 1
	v_addc_co_u32_e32 v151, vcc, 0, v151, vcc
	global_load_dwordx4 v[142:145], v[150:151], off
	global_load_dwordx2 v[146:147], v[150:151], off offset:16
.Lp2c_nosplit:
	v_lshl_add_u64 v[18:19], s[0:1], 0, v[8:9]
	v_add_co_u32_e32 v18, vcc, 0x7600000, v18
	s_mov_b32 s3, 0x5a00000
	s_nop 0
	v_addc_co_u32_e32 v19, vcc, 0, v19, vcc
	global_load_dword v0, v[18:19], off
	global_load_dword v20, v[18:19], off offset:16
	global_load_dword v21, v[18:19], off offset:32
	v_lshl_add_u64 v[90:91], s[0:1], 0, v[16:17]
	v_add_co_u32_e32 v90, vcc, s5, v90
	s_nop 1
	v_addc_co_u32_e32 v91, vcc, 0, v91, vcc
	global_load_dwordx2 v[80:81], v[90:91], off
	global_load_dwordx2 v[82:83], v[90:91], off offset:512
	global_load_dwordx2 v[84:85], v[90:91], off offset:1024
	v_lshl_add_u64 v[92:93], s[0:1], 0, v[14:15]
	v_add_co_u32_e32 v92, vcc, s3, v92
	s_nop 1
	v_addc_co_u32_e32 v93, vcc, 0, v93, vcc
	global_load_dwordx2 v[86:87], v[92:93], off offset:1536
	v_lshl_add_u64 v[94:95], s[0:1], 0, v[10:11]
	v_add_co_u32_e32 v94, vcc, 0x4200000, v94
	s_nop 1
	v_addc_co_u32_e32 v95, vcc, 0, v95, vcc
	global_load_dwordx2 v[88:89], v[94:95], off
	s_bitcmp0_b32 s4, 10
	s_waitcnt vmcnt(5)
	v_max3_f32 v22, v0, v20, v21
	v_sub_f32_e32 v0, v0, v22
	v_mul_f32_e32 v0, 0x3fb8aa3b, v0
	v_exp_f32_e32 v19, v0
	v_sub_f32_e32 v0, v20, v22
	v_mul_f32_e32 v0, 0x3fb8aa3b, v0
	v_exp_f32_e32 v18, v0
	v_sub_f32_e32 v0, v21, v22
	v_mul_f32_e32 v0, 0x3fb8aa3b, v0
	v_exp_f32_e32 v26, v0
	v_add_f32_e32 v0, v19, v18
	v_add_f32_e32 v0, v26, v0
	v_div_scale_f32 v20, s[6:7], v0, v0, 1.0
	v_rcp_f32_e32 v21, v20
	s_nop 0
	v_fma_f32 v22, -v20, v21, 1.0
	v_fmac_f32_e32 v21, v22, v21
	v_div_scale_f32 v22, vcc, 1.0, v0, 1.0
	v_mul_f32_e32 v23, v22, v21
	v_fma_f32 v24, -v20, v23, v22
	v_fmac_f32_e32 v23, v24, v21
	v_fma_f32 v20, -v20, v23, v22
	v_div_fmas_f32 v20, v20, v21, v23
	v_div_fixup_f32 v0, v20, v0, 1.0
	v_pk_mul_f32 v[18:19], v[18:19], v[0:1] op_sel_hi:[1,0]
	v_mul_f32_e32 v26, v26, v0
	s_waitcnt vmcnt(2)
	v_mov_b64_e32 v[22:23], v[80:81]
	v_mov_b64_e32 v[24:25], v[82:83]
	v_mov_b64_e32 v[20:21], v[84:85]
	v_lshlrev_b32_e32 v30, 16, v22
	v_and_b32_e32 v31, 0xffff0000, v24
	v_lshlrev_b32_e32 v28, 16, v24
	v_and_b32_e32 v29, 0xffff0000, v22
	v_pk_mul_f32 v[30:31], v[18:19], v[30:31] op_sel:[1,0] op_sel_hi:[0,1]
	v_lshlrev_b32_e32 v32, 16, v20
	v_and_b32_e32 v33, 0xffff0000, v20
	v_pk_fma_f32 v[28:29], v[18:19], v[28:29], v[30:31]
	v_lshlrev_b32_e32 v22, 16, v23
	v_pk_fma_f32 v[28:29], v[26:27], v[32:33], v[28:29] op_sel_hi:[0,1,1]
	v_cvt_pk_bf16_f32 v20, v28, v29
	v_and_b32_e32 v29, 0xffff0000, v23
	v_and_b32_e32 v23, 0xffff0000, v25
	v_lshlrev_b32_e32 v28, 16, v25
	v_pk_mul_f32 v[22:23], v[18:19], v[22:23] op_sel:[1,0] op_sel_hi:[0,1]
	v_pk_fma_f32 v[18:19], v[18:19], v[28:29], v[22:23]
	v_lshlrev_b32_e32 v22, 16, v21
	v_and_b32_e32 v23, 0xffff0000, v21
	v_pk_fma_f32 v[18:19], v[26:27], v[22:23], v[18:19] op_sel_hi:[0,1,1]
	v_cvt_pk_bf16_f32 v21, v18, v19
	v_lshl_add_u64 v[18:19], s[0:1], 0, v[14:15]
	v_add_co_u32_e32 v22, vcc, s3, v18
	v_lshl_add_u64 v[30:31], s[0:1], 0, v[10:11]
	s_nop 0
	v_addc_co_u32_e32 v23, vcc, 0, v19, vcc
	s_mov_b32 s3, 0x4200000
	global_store_dwordx2 v[22:23], v[20:21], off offset:512
	s_waitcnt vmcnt(1)
	v_mov_b64_e32 v[22:23], v[86:87]
	v_mov_b64_e32 v[26:27], v[88:89]
	v_lshlrev_b32_e32 v20, 16, v22
	v_and_b32_e32 v21, 0xffff0000, v22
	v_lshlrev_b32_e32 v22, 16, v23
	v_and_b32_e32 v23, 0xffff0000, v23
	v_and_b32_e32 v24, 0xffff0000, v26
	v_lshlrev_b32_e32 v25, 16, v26
	v_and_b32_e32 v26, 0xffff0000, v27
	v_lshlrev_b32_e32 v27, 16, v27
	s_cbranch_scc1 .LBB0_527
	v_add_co_u32_e32 v28, vcc, 0x5a00000, v18
	s_nop 0
	v_addc_co_u32_e32 v29, vcc, 0, v19, vcc
	v_mov_b64_e32 v[42:43], v[130:131]
	v_mov_b64_e32 v[34:35], v[132:133]
	v_mov_b64_e32 v[44:45], v[134:135]
	v_mov_b64_e32 v[30:31], v[136:137]
	v_mov_b64_e32 v[38:39], v[142:143]
	v_mov_b64_e32 v[40:41], v[144:145]
	v_mov_b64_e32 v[36:37], v[146:147]
	s_waitcnt vmcnt(1)
	v_max_f32_e32 v0, v39, v39
	v_max_f32_e32 v32, v38, v38
	v_max_f32_e32 v0, v32, v0
	v_sub_f32_e32 v32, v38, v0
	v_sub_f32_e32 v0, v39, v0
	v_exp_f32_e32 v33, v32
	v_exp_f32_e32 v32, v0
	s_nop 0
	v_add_f32_e32 v0, v33, v32
	v_div_scale_f32 v38, s[6:7], v0, v0, 1.0
	v_rcp_f32_e32 v39, v38
	s_nop 0
	v_fma_f32 v46, -v38, v39, 1.0
	v_fmac_f32_e32 v39, v46, v39
	v_div_scale_f32 v46, vcc, 1.0, v0, 1.0
	v_mul_f32_e32 v47, v46, v39
	v_fma_f32 v48, -v38, v47, v46
	v_fmac_f32_e32 v47, v48, v39
	v_fma_f32 v38, -v38, v47, v46
	v_div_fmas_f32 v38, v38, v39, v47
	v_div_fixup_f32 v0, v38, v0, 1.0
	v_pk_mul_f32 v[38:39], v[32:33], v[0:1] op_sel_hi:[1,0]
	v_lshlrev_b32_e32 v46, 16, v34
	v_and_b32_e32 v47, 0xffff0000, v42
	v_lshlrev_b32_e32 v32, 16, v42
	v_and_b32_e32 v33, 0xffff0000, v34
	v_pk_mul_f32 v[46:47], v[38:39], v[46:47] op_sel:[1,0] op_sel_hi:[0,1]
	v_pk_fma_f32 v[32:33], v[38:39], v[32:33], v[46:47]
	v_and_b32_e32 v47, 0xffff0000, v35
	v_lshlrev_b32_e32 v34, 16, v35
	v_and_b32_e32 v35, 0xffff0000, v43
	v_lshlrev_b32_e32 v46, 16, v43
	v_pk_mul_f32 v[34:35], v[38:39], v[34:35] op_sel:[1,0] op_sel_hi:[0,1]
	v_pk_fma_f32 v[34:35], v[38:39], v[46:47], v[34:35]
	v_max_f32_e32 v0, v41, v41
	v_max_f32_e32 v38, v40, v40
	v_max_f32_e32 v0, v38, v0
	v_sub_f32_e32 v38, v40, v0
	v_sub_f32_e32 v0, v41, v0
	v_exp_f32_e32 v38, v38
	v_exp_f32_e32 v39, v0
	s_nop 0
	v_add_f32_e32 v0, v38, v39
	v_div_scale_f32 v40, s[6:7], v0, v0, 1.0
	v_rcp_f32_e32 v41, v40
	s_nop 0
	v_fma_f32 v42, -v40, v41, 1.0
	v_fmac_f32_e32 v41, v42, v41
	v_div_scale_f32 v42, vcc, 1.0, v0, 1.0
	v_mul_f32_e32 v43, v42, v41
	v_fma_f32 v46, -v40, v43, v42
	v_fmac_f32_e32 v43, v46, v41
	v_fma_f32 v40, -v40, v43, v42
	v_div_fmas_f32 v40, v40, v41, v43
	v_div_fixup_f32 v40, v40, v0, 1.0
	v_mul_f32_e32 v0, v38, v40
	v_mul_f32_e32 v38, v39, v40
	v_lshlrev_b32_e32 v40, 16, v44
	v_and_b32_e32 v41, 0xffff0000, v44
	v_pk_mul_f32 v[40:41], v[38:39], v[40:41] op_sel_hi:[0,1]
	v_pk_fma_f32 v[20:21], v[0:1], v[20:21], v[40:41] op_sel_hi:[0,1,1]
	v_lshlrev_b32_e32 v40, 16, v45
	v_and_b32_e32 v41, 0xffff0000, v45
	v_pk_mul_f32 v[38:39], v[38:39], v[40:41] op_sel_hi:[0,1]
	v_pk_fma_f32 v[22:23], v[0:1], v[22:23], v[38:39] op_sel_hi:[0,1,1]
	s_waitcnt vmcnt(0)
	v_max_f32_e32 v0, v37, v37
	v_max_f32_e32 v38, v36, v36
	v_max_f32_e32 v0, v38, v0
	v_sub_f32_e32 v36, v36, v0
	v_sub_f32_e32 v0, v37, v0
	v_exp_f32_e32 v36, v36
	v_exp_f32_e32 v37, v0
	s_nop 0
	v_add_f32_e32 v0, v36, v37
	v_div_scale_f32 v38, s[6:7], v0, v0, 1.0
	v_rcp_f32_e32 v39, v38
	s_nop 0
	v_fma_f32 v40, -v38, v39, 1.0
	v_fmac_f32_e32 v39, v40, v39
	v_div_scale_f32 v40, vcc, 1.0, v0, 1.0
	v_mul_f32_e32 v41, v40, v39
	v_fma_f32 v42, -v38, v41, v40
	v_fmac_f32_e32 v41, v42, v39
	v_fma_f32 v38, -v38, v41, v40
	v_div_fmas_f32 v38, v38, v39, v41
	v_div_fixup_f32 v38, v38, v0, 1.0
	v_mul_f32_e32 v0, v36, v38
	v_mul_f32_e32 v36, v37, v38
	v_and_b32_e32 v38, 0xffff0000, v30
	v_lshlrev_b32_e32 v39, 16, v30
	v_and_b32_e32 v30, 0xffff0000, v31
	v_lshlrev_b32_e32 v31, 16, v31
	v_pk_mul_f32 v[38:39], v[36:37], v[38:39] op_sel_hi:[0,1]
	v_pk_mul_f32 v[30:31], v[36:37], v[30:31] op_sel_hi:[0,1]
	v_pk_fma_f32 v[24:25], v[0:1], v[24:25], v[38:39] op_sel_hi:[0,1,1]
	v_pk_fma_f32 v[26:27], v[0:1], v[26:27], v[30:31] op_sel_hi:[0,1,1]
	v_cvt_pk_bf16_f32 v30, v32, v33
	v_cvt_pk_bf16_f32 v31, v34, v35
	global_store_dwordx2 v[28:29], v[30:31], off offset:1024
	s_branch .LBB0_527
